# static priority raise for waves 4-7 also in the three prompt memory-attention unit instances
# baseline (speedup 1.0000x reference)
; #define LAS __attribute__((address_space(3)))
; DI int q_next(gu32* ctr, volatile LAS int* slot, int tid) {
;     __syncthreads();
;     if (tid == 0) *slot = (int)__hip_atomic_fetch_add(ctr, 1u, RLX_AGENT);
;     __syncthreads();
;     return *slot;
.LBB0_497:
	s_setprio 0
	s_barrier
	s_and_saveexec_b64 s[2:3], s[56:57]
	s_cbranch_execz .LBB0_501
	s_mov_b64 s[14:15], exec
	v_mbcnt_lo_u32_b32 v2, s14, 0
	v_mbcnt_hi_u32_b32 v2, s15, v2
	v_cmp_eq_u32_e32 vcc, 0, v2
	s_and_saveexec_b64 s[12:13], vcc
	s_cbranch_execz .LBB0_500
	s_bcnt1_i32_b64 s4, s[14:15]
	v_mov_b32_e32 v4, s4
	global_atomic_add v4, v3, v4, s[0:1] sc0

; DI f32x4 unpack4(v2u w) { return (f32x4){bflo(w.x), bfhi(w.x), bflo(w.y), bfhi(w.y)}; }
; DI void unit_memattn(int u, const bf16* __restrict__ MQ, const bf16* __restrict__ MK, const bf16* __restrict__ MV, const bf16* __restrict__ G, bf16* __restrict__ MIX, const bf16* __restrict__ CB, const bf16* __restrict__ U, const float* __restrict__ convw, ...
;     asm volatile("" : "+v"(lane), "+v"(tid));
;     const int b = u >> 7, hm = (u >> 5) & 3, qb = u & 31;
;     const long goff0 = ((long)b * 256) * 256 + hm * 64;
;     v4u fk[4], fv[4], gv[4];
; #pragma unroll
;     for (int i = 0; i < 4; ++i) { const int id = tid + NT * i, j = id >> 3, ch = id & 7;
;         fk[i] = *(const v4u*)(MK + goff0 + (long)j * 256 + ch * 8); fv[i] = *(const v4u*)(MV + goff0 + (long)j * 256 + ch * 8);
;         gv[i] = *(const v4u*)(G + ((size_t)b * SEQ + qb * 256 + j) * D + 768 + hm * 64 + ch * 8); }
;     {   const int c4 = hm * 64 + (tid & 15) * 4;
;         const f32x4 w0 = *(const f32x4*)(convw + c4), w1 = *(const f32x4*)(convw + 256 + c4), w2 = *(const f32x4*)(convw + 512 + c4);
; #pragma unroll 4
;         for (int rl = tid >> 4; rl < 256; rl += NT / 16) { const size_t r2 = (size_t)b * SEQ + qb * 256 + rl; const int t = (int)(r2 & (SEQ - 1));
;             const f32x4 cb = unpack4(*(const v2u*)(CB + r2 * 256 + c4)), u0 = unpack4(*(const v2u*)(U + r2 * 256 + c4));
;             f32x4 u1 = (f32x4){0.f, 0.f, 0.f, 0.f}, u2 = u1;
;             if (t >= 1) u1 = unpack4(*(const v2u*)(U + (r2 - 1) * 256 + c4));
.LBB0_501:
	s_or_b64 exec, exec, s[2:3]
	s_waitcnt lgkmcnt(0)
	s_barrier
	ds_read_b32 v2, v1
	s_xor_b64 s[10:11], s[10:11], -1
	s_waitcnt lgkmcnt(0)
	v_readfirstlane_b32 s3, v2
	s_cmpk_gt_i32 s3, 0xff
	s_cbranch_scc1 .LBB0_496
	s_cmp_lt_u32 s33, 4
	s_cbranch_scc1 .Lx1prio_lo
	s_setprio 2
.Lx1prio_lo:
	s_ashr_i32 s12, s3, 7
	s_lshl_b32 s2, s3, 1
	s_ashr_i32 s13, s12, 31
	s_and_b32 s2, s2, 0xc0
	s_lshl_b64 s[14:15], s[12:13], 17
	s_lshl_b32 s4, s2, 1
	s_or_b32 s14, s14, s4
	v_mov_b32_e32 v153, v182
	v_mov_b32_e32 v152, v0
	s_add_u32 s16, s64, s14
	s_addc_u32 s17, s65, s15
	v_lshlrev_b32_e32 v2, 3, v152
	v_and_b32_e32 v2, 56, v2
	s_add_u32 s14, s66, s14
	v_lshlrev_b32_e32 v132, 1, v2
	v_mov_b32_e32 v133, v3
	s_addc_u32 s15, s67, s15
	s_lshl_b32 s3, s3, 8
	v_lshl_add_u64 v[28:29], s[16:17], 0, v[132:133]
	s_lshl_b64 s[16:17], s[12:13], 13
	s_and_b32 s13, s3, 0x1f00
	v_ashrrev_i32_e32 v142, 3, v152
	v_lshl_add_u64 v[32:33], s[14:15], 0, v[132:133]
	s_or_b32 s14, s16, s13
	s_mov_b32 s15, s17
	v_ashrrev_i32_e32 v143, 31, v142
	v_lshlrev_b64 v[4:5], 9, v[142:143]
	v_lshl_add_u64 v[12:13], s[14:15], 0, v[142:143]
	v_add_u32_e32 v143, 0x200, v152
	v_ashrrev_i32_e32 v144, 3, v143
	v_ashrrev_i32_e32 v145, 31, v144
	v_lshl_add_u64 v[18:19], s[14:15], 0, v[144:145]
	v_lshlrev_b64 v[140:141], 11, v[12:13]
	v_lshlrev_b64 v[138:139], 11, v[18:19]
	v_lshl_add_u64 v[12:13], s[24:25], 0, v[140:141]
	v_lshlrev_b64 v[16:17], 9, v[144:145]
	v_lshl_add_u64 v[18:19], s[24:25], 0, v[138:139]
	v_add_u32_e32 v145, 0x400, v152
	v_lshl_add_u64 v[12:13], v[12:13], 0, s[4:5]
	v_lshl_add_u64 v[18:19], v[18:19], 0, s[4:5]
	v_ashrrev_i32_e32 v146, 3, v145
	v_lshl_add_u64 v[6:7], v[28:29], 0, v[4:5]
	v_lshl_add_u64 v[8:9], v[32:33], 0, v[4:5]
	v_lshl_add_u64 v[12:13], v[12:13], 0, v[132:133]
	v_lshl_add_u64 v[14:15], v[28:29], 0, v[16:17]
	v_lshl_add_u64 v[16:17], v[32:33], 0, v[16:17]
	v_lshl_add_u64 v[20:21], v[18:19], 0, v[132:133]
	v_ashrrev_i32_e32 v147, 31, v146
	global_load_dwordx4 v[4:7], v[6:7], off
	s_nop 0
	global_load_dwordx4 v[8:11], v[8:9], off
	s_nop 0
	global_load_dwordx4 v[80:83], v[12:13], off offset:1536
	s_nop 0
	global_load_dwordx4 v[12:15], v[14:15], off
	s_nop 0
	global_load_dwordx4 v[16:19], v[16:17], off
	s_nop 0
	global_load_dwordx4 v[76:79], v[20:21], off offset:1536
	v_lshlrev_b64 v[20:21], 9, v[146:147]
	v_lshl_add_u64 v[30:31], s[14:15], 0, v[146:147]
	v_add_u32_e32 v147, 0x600, v152
	v_ashrrev_i32_e32 v148, 3, v147
	v_ashrrev_i32_e32 v149, 31, v148
	v_lshlrev_b64 v[34:35], 9, v[148:149]
	v_lshl_add_u64 v[22:23], v[28:29], 0, v[20:21]
	v_lshl_add_u64 v[24:25], v[32:33], 0, v[20:21]
	v_lshlrev_b64 v[136:137], 11, v[30:31]
	v_lshl_add_u64 v[28:29], v[28:29], 0, v[34:35]
	v_lshl_add_u64 v[32:33], v[32:33], 0, v[34:35]
	v_lshl_add_u64 v[34:35], s[14:15], 0, v[148:149]
	v_lshl_add_u64 v[30:31], s[24:25], 0, v[136:137]
	v_lshlrev_b64 v[134:135], 11, v[34:35]
	v_lshl_add_u64 v[30:31], v[30:31], 0, s[4:5]
	v_lshl_add_u64 v[34:35], s[24:25], 0, v[134:135]
	v_lshl_add_u64 v[30:31], v[30:31], 0, v[132:133]
	v_lshl_add_u64 v[34:35], v[34:35], 0, s[4:5]
	global_load_dwordx4 v[20:23], v[22:23], off
	s_nop 0
	global_load_dwordx4 v[24:27], v[24:25], off
	s_nop 0
	global_load_dwordx4 v[72:75], v[30:31], off offset:1536
	s_nop 0
	global_load_dwordx4 v[28:31], v[28:29], off
	v_lshl_add_u64 v[36:37], v[34:35], 0, v[132:133]
	global_load_dwordx4 v[32:35], v[32:33], off
	s_nop 0
	global_load_dwordx4 v[68:71], v[36:37], off offset:1536
	v_ashrrev_i32_e32 v60, 4, v152
	s_movk_i32 s3, 0x100
	v_cmp_gt_i32_e32 vcc, s3, v60
	s_and_saveexec_b64 s[14:15], vcc
	s_cbranch_execz .LBB0_530
	v_lshlrev_b32_e32 v2, 2, v152
	v_and_or_b32 v84, v2, 60, s2
	v_readlane_b32 s40, v247, 25
	v_lshlrev_b32_e32 v2, 2, v84
	v_readlane_b32 s44, v247, 29
	v_readlane_b32 s45, v247, 30
	s_nop 4
	global_load_dwordx4 v[36:39], v2, s[44:45]
	global_load_dwordx4 v[40:43], v2, s[44:45] offset:1024
	global_load_dwordx4 v[44:47], v2, s[44:45] offset:2048
	v_max_i32_e32 v2, 0xe0, v60
	v_sub_u32_e32 v2, v2, v60
	v_add_u32_e32 v85, 31, v2
	v_and_b32_e32 v2, 0x60, v85
	v_cmp_ne_u32_e32 vcc, s27, v2
	v_readlane_b32 s41, v247, 26
	v_readlane_b32 s42, v247, 27
	v_readlane_b32 s43, v247, 28
	v_readlane_b32 s46, v247, 31
	v_readlane_b32 s47, v247, 32
	v_readlane_b32 s48, v247, 33
	v_readlane_b32 s49, v247, 34
	v_readlane_b32 s50, v247, 35
	v_readlane_b32 s51, v247, 36
	v_readlane_b32 s52, v247, 37
	v_readlane_b32 s53, v247, 38
	v_readlane_b32 s54, v247, 39
	v_readlane_b32 s55, v247, 40
	s_and_saveexec_b64 s[18:19], vcc
	s_cbranch_execz .LBB0_511
	s_add_u32 s2, s16, s13
	v_lshrrev_b32_e32 v2, 5, v85
	s_addc_u32 s3, s17, 0
	v_ashrrev_i32_e32 v61, 31, v60
	v_add_u32_e32 v2, 1, v2
	v_lshl_add_u64 v[50:51], s[2:3], 0, v[60:61]
	v_and_b32_e32 v52, 3, v2
	v_lshlrev_b64 v[48:49], 11, v[50:51]
	v_lshlrev_b64 v[50:51], 9, v[50:51]
	s_lshl_b32 s2, s12, 13
	v_lshlrev_b32_e32 v2, 1, v84
	v_lshl_add_u64 v[48:49], s[82:83], 0, v[48:49]
	v_lshl_add_u64 v[50:51], s[82:83], 0, v[50:51]
	v_sub_u32_e32 v61, 0, v52
	s_or_b32 s39, s2, s13
	s_mov_b64 s[20:21], 0
	s_branch .LBB0_506

; DI f32x4 unpack4(v2u w) { return (f32x4){bflo(w.x), bfhi(w.x), bflo(w.y), bfhi(w.y)}; }
; DI void unit_memattn(int u, const bf16* __restrict__ MQ, const bf16* __restrict__ MK, const bf16* __restrict__ MV, const bf16* __restrict__ G, bf16* __restrict__ MIX, const bf16* __restrict__ CB, const bf16* __restrict__ U, const float* __restrict__ convw, ...
;     asm volatile("" : "+v"(lane), "+v"(tid));
;     const int b = u >> 7, hm = (u >> 5) & 3, qb = u & 31;
;     const long goff0 = ((long)b * 256) * 256 + hm * 64;
;     v4u fk[4], fv[4], gv[4];
; #pragma unroll
;     for (int i = 0; i < 4; ++i) { const int id = tid + NT * i, j = id >> 3, ch = id & 7;
;         fk[i] = *(const v4u*)(MK + goff0 + (long)j * 256 + ch * 8); fv[i] = *(const v4u*)(MV + goff0 + (long)j * 256 + ch * 8);
;         gv[i] = *(const v4u*)(G + ((size_t)b * SEQ + qb * 256 + j) * D + 768 + hm * 64 + ch * 8); }
;     {   const int c4 = hm * 64 + (tid & 15) * 4;
;         const f32x4 w0 = *(const f32x4*)(convw + c4), w1 = *(const f32x4*)(convw + 256 + c4), w2 = *(const f32x4*)(convw + 512 + c4);
; #pragma unroll 4
;         for (int rl = tid >> 4; rl < 256; rl += NT / 16) { const size_t r2 = (size_t)b * SEQ + qb * 256 + rl; const int t = (int)(r2 & (SEQ - 1));
;             const f32x4 cb = unpack4(*(const v2u*)(CB + r2 * 256 + c4)), u0 = unpack4(*(const v2u*)(U + r2 * 256 + c4));
;             f32x4 u1 = (f32x4){0.f, 0.f, 0.f, 0.f}, u2 = u1;
;             if (t >= 1) u1 = unpack4(*(const v2u*)(U + (r2 - 1) * 256 + c4));
.LBB0_646:
	s_and_b64 vcc, exec, s[2:3]
	s_cbranch_vccz .LBB0_645
	s_cmp_lt_u32 s33, 4
	s_cbranch_scc1 .Lx2prio_lo
	s_setprio 2
.Lx2prio_lo:
	s_ashr_i32 s10, s12, 7
	s_lshl_b32 s0, s12, 1
	s_ashr_i32 s11, s10, 31
	s_and_b32 s2, s0, 0xc0
	s_lshl_b64 s[0:1], s[10:11], 17
	s_lshl_b32 s8, s2, 1
	s_or_b32 s0, s0, s8
	v_mov_b32_e32 v150, v182
	v_mov_b32_e32 v1, v0
	s_add_u32 s14, s64, s0
	s_addc_u32 s15, s65, s1
	v_lshlrev_b32_e32 v2, 3, v1
	v_and_b32_e32 v2, 56, v2
	s_add_u32 s0, s66, s0
	v_mov_b32_e32 v131, 0
	v_lshlrev_b32_e32 v130, 1, v2
	s_addc_u32 s1, s67, s1
	s_lshl_b32 s3, s12, 8
	v_lshl_add_u64 v[30:31], s[0:1], 0, v[130:131]
	s_lshl_b64 s[0:1], s[10:11], 13
	s_and_b32 s11, s3, 0x1f00
	v_ashrrev_i32_e32 v140, 3, v1
	s_or_b32 s12, s0, s11
	s_mov_b32 s13, s1
	v_ashrrev_i32_e32 v141, 31, v140
	v_lshlrev_b64 v[2:3], 9, v[140:141]
	v_lshl_add_u64 v[10:11], s[12:13], 0, v[140:141]
	v_add_u32_e32 v141, 0x200, v1
	v_ashrrev_i32_e32 v142, 3, v141
	v_ashrrev_i32_e32 v143, 31, v142
	v_lshl_add_u64 v[16:17], s[12:13], 0, v[142:143]
	v_lshlrev_b64 v[138:139], 11, v[10:11]
	v_lshlrev_b64 v[136:137], 11, v[16:17]
	s_mov_b32 s9, 0
	v_lshl_add_u64 v[10:11], s[24:25], 0, v[138:139]
	v_lshlrev_b64 v[14:15], 9, v[142:143]
	v_lshl_add_u64 v[16:17], s[24:25], 0, v[136:137]
	v_add_u32_e32 v143, 0x400, v1
	v_lshl_add_u64 v[26:27], s[14:15], 0, v[130:131]
	v_lshl_add_u64 v[10:11], v[10:11], 0, s[8:9]
	v_lshl_add_u64 v[16:17], v[16:17], 0, s[8:9]
	v_ashrrev_i32_e32 v144, 3, v143
	v_lshl_add_u64 v[4:5], v[26:27], 0, v[2:3]
	v_lshl_add_u64 v[6:7], v[30:31], 0, v[2:3]
	v_lshl_add_u64 v[10:11], v[10:11], 0, v[130:131]
	v_lshl_add_u64 v[12:13], v[26:27], 0, v[14:15]
	v_lshl_add_u64 v[14:15], v[30:31], 0, v[14:15]
	v_lshl_add_u64 v[18:19], v[16:17], 0, v[130:131]
	v_ashrrev_i32_e32 v145, 31, v144
	global_load_dwordx4 v[2:5], v[4:5], off
	s_nop 0
	global_load_dwordx4 v[6:9], v[6:7], off
	s_nop 0
	global_load_dwordx4 v[78:81], v[10:11], off offset:1536
	s_nop 0
	global_load_dwordx4 v[10:13], v[12:13], off
	s_nop 0
	global_load_dwordx4 v[14:17], v[14:15], off
	s_nop 0
	global_load_dwordx4 v[74:77], v[18:19], off offset:1536
	v_lshlrev_b64 v[18:19], 9, v[144:145]
	v_lshl_add_u64 v[28:29], s[12:13], 0, v[144:145]
	v_add_u32_e32 v145, 0x600, v1
	v_ashrrev_i32_e32 v146, 3, v145
	v_ashrrev_i32_e32 v147, 31, v146
	v_lshlrev_b64 v[32:33], 9, v[146:147]
	v_lshl_add_u64 v[20:21], v[26:27], 0, v[18:19]
	v_lshl_add_u64 v[22:23], v[30:31], 0, v[18:19]
	v_lshlrev_b64 v[134:135], 11, v[28:29]
	v_lshl_add_u64 v[26:27], v[26:27], 0, v[32:33]
	v_lshl_add_u64 v[30:31], v[30:31], 0, v[32:33]
	v_lshl_add_u64 v[32:33], s[12:13], 0, v[146:147]
	v_lshl_add_u64 v[28:29], s[24:25], 0, v[134:135]
	v_lshlrev_b64 v[132:133], 11, v[32:33]
	v_lshl_add_u64 v[28:29], v[28:29], 0, s[8:9]
	v_lshl_add_u64 v[32:33], s[24:25], 0, v[132:133]
	v_lshl_add_u64 v[28:29], v[28:29], 0, v[130:131]
	v_lshl_add_u64 v[32:33], v[32:33], 0, s[8:9]
	global_load_dwordx4 v[18:21], v[20:21], off
	s_nop 0
	global_load_dwordx4 v[22:25], v[22:23], off
	s_nop 0
	global_load_dwordx4 v[70:73], v[28:29], off offset:1536
	s_nop 0
	global_load_dwordx4 v[26:29], v[26:27], off
	v_lshl_add_u64 v[34:35], v[32:33], 0, v[130:131]
	global_load_dwordx4 v[30:33], v[30:31], off
	s_nop 0
	global_load_dwordx4 v[66:69], v[34:35], off offset:1536
	v_ashrrev_i32_e32 v60, 4, v1
	s_movk_i32 s3, 0x100
	v_cmp_gt_i32_e32 vcc, s3, v60
	s_and_saveexec_b64 s[12:13], vcc
	s_cbranch_execz .LBB0_675
	v_lshlrev_b32_e32 v34, 2, v1
	v_and_or_b32 v84, v34, 60, s2
	v_readlane_b32 s40, v247, 25
	v_lshlrev_b32_e32 v42, 2, v84
	v_readlane_b32 s44, v247, 29
	v_readlane_b32 s45, v247, 30
	s_nop 4
	global_load_dwordx4 v[34:37], v42, s[44:45]
	global_load_dwordx4 v[38:41], v42, s[44:45] offset:1024
	s_nop 0
	global_load_dwordx4 v[42:45], v42, s[44:45] offset:2048
	v_max_i32_e32 v46, 0xe0, v60
	v_sub_u32_e32 v46, v46, v60
	v_add_u32_e32 v85, 31, v46
	s_movk_i32 s2, 0x60
	v_and_b32_e32 v46, 0x60, v85
	v_cmp_ne_u32_e32 vcc, s2, v46
	v_readlane_b32 s41, v247, 26
	v_readlane_b32 s42, v247, 27
	v_readlane_b32 s43, v247, 28
	v_readlane_b32 s46, v247, 31
	v_readlane_b32 s47, v247, 32
	v_readlane_b32 s48, v247, 33
	v_readlane_b32 s49, v247, 34
	v_readlane_b32 s50, v247, 35
	v_readlane_b32 s51, v247, 36
	v_readlane_b32 s52, v247, 37
	v_readlane_b32 s53, v247, 38
	v_readlane_b32 s54, v247, 39
	v_readlane_b32 s55, v247, 40
	s_and_saveexec_b64 s[14:15], vcc
	s_cbranch_execz .LBB0_656
	s_add_u32 s2, s0, s11
	v_lshrrev_b32_e32 v46, 5, v85
	s_addc_u32 s3, s1, 0
	v_ashrrev_i32_e32 v61, 31, v60
	v_add_u32_e32 v46, 1, v46
	v_lshl_add_u64 v[50:51], s[2:3], 0, v[60:61]
	v_and_b32_e32 v52, 3, v46
	v_lshlrev_b64 v[48:49], 11, v[50:51]
	v_lshlrev_b64 v[50:51], 9, v[50:51]
	s_lshl_b32 s2, s10, 13
	v_lshlrev_b32_e32 v46, 1, v84
	v_mov_b32_e32 v47, 0
	v_lshl_add_u64 v[48:49], s[82:83], 0, v[48:49]
	v_lshl_add_u64 v[50:51], s[82:83], 0, v[50:51]
	v_sub_u32_e32 v61, 0, v52
	s_or_b32 s9, s2, s11
	s_mov_b64 s[16:17], 0
	s_mov_b32 s22, 0x8800000
	s_mov_b64 s[18:19], 0x10000
	s_mov_b64 s[20:21], 0x4000
	s_branch .LBB0_651

; #define LAS __attribute__((address_space(3)))
; DI v2u pack4(f32x4 a) { v2u w; w.x = cvtpk(a[0], a[1]); w.y = cvtpk(a[2], a[3]); return w; }
; DI void unit_memattn(int u, const bf16* __restrict__ MQ, const bf16* __restrict__ MK, const bf16* __restrict__ MV, const bf16* __restrict__ G, bf16* __restrict__ MIX, const bf16* __restrict__ CB, const bf16* __restrict__ U, const float* __restrict__ convw, ...
;     ...
;     {
;         const float inv = 1.f / l; const int rl = 32 * wave + qq, sw = (rl ^ (rl >> 3) ^ (rl >> 6)) & 7;
;         LAS unsigned char* ob = lds + 94208 + rl * 128 + 8 * hh;
; #pragma unroll
;         for (int g = 0; g < 4; ++g) {
;             *(LAS v2u*)(ob + ((g ^ sw) << 4)) = pack4((f32x4){o0[4 * g], o0[4 * g + 1], o0[4 * g + 2], o0[4 * g + 3]} * inv);
;             *(LAS v2u*)(ob + (((4 + g) ^ sw) << 4)) = pack4((f32x4){o1[4 * g], o1[4 * g + 1], o1[4 * g + 2], o1[4 * g + 3]} * inv); }
;     }
;     __syncthreads();
;     {   v4u ov[4];
; #pragma unroll
;         for (int i = 0; i < 4; ++i) { const int id = tid + NT * i, rl = id >> 3, c = id & 7;
;             ov[i] = *(LAS const v4u*)(lds + 94208 + rl * 128 + ((c ^ ((rl ^ (rl >> 3) ^ (rl >> 6)) & 7)) << 4)); }
.LBB0_680:
	v_div_scale_f32 v34, s[2:3], v151, v151, 1.0
	v_rcp_f32_e32 v35, v34
	v_div_scale_f32 v36, vcc, 1.0, v151, 1.0
	s_movk_i32 s2, 0x50
	v_fma_f32 v37, -v34, v35, 1.0
	v_fmac_f32_e32 v35, v37, v35
	v_mul_f32_e32 v37, v36, v35
	v_fma_f32 v38, -v34, v37, v36
	v_fmac_f32_e32 v37, v38, v35
	v_fma_f32 v34, -v34, v37, v36
	v_div_fmas_f32 v34, v34, v35, v37
	v_or_b32_e32 v35, s0, v131
	v_lshrrev_b32_e32 v36, 3, v35
	s_lshr_b32 s0, s84, 7
	v_xor_b32_e32 v36, s0, v36
	v_lshlrev_b32_e32 v35, 7, v35
	s_add_i32 s0, 0, 0x17000
	v_div_fixup_f32 v34, v34, v151, 1.0
	v_add3_u32 v35, s0, v35, v148
	v_xor_b32_e32 v36, v36, v150
	v_pk_mul_f32 v[4:5], v[34:35], v[4:5] op_sel_hi:[0,1]
	v_pk_mul_f32 v[2:3], v[34:35], v[2:3] op_sel_hi:[0,1]
	v_cvt_pk_bf16_f32 v2, v2, v3
	v_cvt_pk_bf16_f32 v3, v4, v5
	v_lshlrev_b32_e32 v4, 4, v36
	v_and_b32_e32 v36, 0x70, v4
	v_add_u32_e32 v4, v35, v36
	ds_write_b64 v4, v[2:3]
	v_pk_mul_f32 v[2:3], v[34:35], v[20:21] op_sel_hi:[0,1]
	v_pk_mul_f32 v[4:5], v[34:35], v[18:19] op_sel_hi:[0,1]
	v_cvt_pk_bf16_f32 v4, v4, v5
	v_cvt_pk_bf16_f32 v5, v2, v3
	v_xad_u32 v2, v36, 64, v35
	ds_write_b64 v2, v[4:5]
	v_pk_mul_f32 v[2:3], v[34:35], v[8:9] op_sel_hi:[0,1]
	v_pk_mul_f32 v[4:5], v[34:35], v[6:7] op_sel_hi:[0,1]
	v_cvt_pk_bf16_f32 v4, v4, v5
	v_cvt_pk_bf16_f32 v5, v2, v3
	v_xad_u32 v2, v36, 16, v35
	ds_write_b64 v2, v[4:5]
	v_pk_mul_f32 v[2:3], v[34:35], v[24:25] op_sel_hi:[0,1]
	v_pk_mul_f32 v[4:5], v[34:35], v[22:23] op_sel_hi:[0,1]
	v_cvt_pk_bf16_f32 v4, v4, v5
	v_cvt_pk_bf16_f32 v5, v2, v3
	v_xad_u32 v2, v36, s2, v35
	ds_write_b64 v2, v[4:5]
	v_pk_mul_f32 v[2:3], v[34:35], v[12:13] op_sel_hi:[0,1]
	v_pk_mul_f32 v[4:5], v[34:35], v[10:11] op_sel_hi:[0,1]
	v_cvt_pk_bf16_f32 v4, v4, v5
	v_cvt_pk_bf16_f32 v5, v2, v3
	v_xad_u32 v2, v36, 32, v35
	ds_write_b64 v2, v[4:5]
	v_pk_mul_f32 v[2:3], v[34:35], v[28:29] op_sel_hi:[0,1]
	v_pk_mul_f32 v[4:5], v[34:35], v[26:27] op_sel_hi:[0,1]
	s_movk_i32 s2, 0x60
	v_cvt_pk_bf16_f32 v4, v4, v5
	v_cvt_pk_bf16_f32 v5, v2, v3
	v_xad_u32 v2, v36, s2, v35
	ds_write_b64 v2, v[4:5]
	v_pk_mul_f32 v[2:3], v[34:35], v[16:17] op_sel_hi:[0,1]
	v_pk_mul_f32 v[4:5], v[34:35], v[14:15] op_sel_hi:[0,1]
	v_cvt_pk_bf16_f32 v4, v4, v5
	v_cvt_pk_bf16_f32 v5, v2, v3
	v_xad_u32 v2, v36, 48, v35
	s_movk_i32 s1, 0x70
	ds_write_b64 v2, v[4:5]
	v_pk_mul_f32 v[2:3], v[34:35], v[32:33] op_sel_hi:[0,1]
	v_pk_mul_f32 v[4:5], v[34:35], v[30:31] op_sel_hi:[0,1]
	v_cvt_pk_bf16_f32 v4, v4, v5
	v_cvt_pk_bf16_f32 v5, v2, v3
	v_xad_u32 v2, v36, s1, v35
	v_lshrrev_b32_e32 v3, 9, v1
	ds_write_b64 v2, v[4:5]
	v_lshrrev_b32_e32 v10, 6, v1
	v_xor_b32_e32 v3, v1, v3
	v_lshrrev_b32_e32 v4, 9, v141
	v_xor_b32_e32 v3, v3, v10
	v_xor_b32_e32 v4, v1, v4
	v_xor_b32_e32 v3, v3, v140
	v_xor_b32_e32 v4, v4, v10
	v_lshlrev_b32_e32 v3, 4, v3
	v_xor_b32_e32 v4, v4, v142
	v_lshlrev_b32_e32 v2, 7, v140
	v_and_b32_e32 v3, 0x70, v3
	v_lshlrev_b32_e32 v4, 4, v4
	v_add3_u32 v2, s0, v2, v3
	v_lshlrev_b32_e32 v3, 7, v142
	v_and_b32_e32 v4, 0x70, v4
	v_add3_u32 v6, s0, v3, v4
	s_waitcnt lgkmcnt(0)
	s_barrier
; #define LAS __attribute__((address_space(3)))
; DI unsigned cvtpk(float lo, float hi) { f32x2_t v = {lo, hi}; bf16x2_t b = __builtin_convertvector(v, bf16x2_t); return __builtin_bit_cast(unsigned, b); }
; DI void unit_memattn(int u, const bf16* __restrict__ MQ, const bf16* __restrict__ MK, const bf16* __restrict__ MV, const bf16* __restrict__ G, bf16* __restrict__ MIX, const bf16* __restrict__ CB, const bf16* __restrict__ U, const float* __restrict__ convw, ...
;     ...
;     {   v4u ov[4];
; #pragma unroll
;         for (int i = 0; i < 4; ++i) { const int id = tid + NT * i, rl = id >> 3, c = id & 7;
;             ov[i] = *(LAS const v4u*)(lds + 94208 + rl * 128 + ((c ^ ((rl ^ (rl >> 3) ^ (rl >> 6)) & 7)) << 4)); }
; #pragma unroll
;         for (int i = 0; i < 4; ++i) { const int id = tid + NT * i, rl = id >> 3, c = id & 7; v4u w;
; #pragma unroll
;             for (int e = 0; e < 4; ++e) w[e] = cvtpk(bflo(ov[i][e]) * bflo(gv[i][e]), bfhi(ov[i][e]) * bfhi(gv[i][e]));
;             *(v4u*)(MIX + ((size_t)b * SEQ + qb * 256 + rl) * D + 768 + hm * 64 + c * 8) = w; }
;     }
	ds_read_b128 v[2:5], v2
	ds_read_b128 v[6:9], v6
	v_lshlrev_b32_e32 v20, 16, v78
	v_and_b32_e32 v21, 0xffff0000, v78
	v_lshrrev_b32_e32 v12, 9, v143
	s_waitcnt lgkmcnt(1)
	v_lshlrev_b32_e32 v18, 16, v2
	v_and_b32_e32 v19, 0xffff0000, v2
	v_pk_mul_f32 v[18:19], v[20:21], v[18:19]
	v_lshlrev_b32_e32 v20, 16, v79
	v_cvt_pk_bf16_f32 v2, v18, v19
	v_lshlrev_b32_e32 v18, 16, v3
	v_and_b32_e32 v19, 0xffff0000, v3
	v_and_b32_e32 v21, 0xffff0000, v79
	v_pk_mul_f32 v[18:19], v[20:21], v[18:19]
	v_lshlrev_b32_e32 v20, 16, v80
	v_cvt_pk_bf16_f32 v3, v18, v19
	v_lshlrev_b32_e32 v18, 16, v4
	v_and_b32_e32 v19, 0xffff0000, v4
	v_and_b32_e32 v21, 0xffff0000, v80
	v_xor_b32_e32 v12, v1, v12
	v_lshrrev_b32_e32 v13, 9, v145
	v_pk_mul_f32 v[18:19], v[20:21], v[18:19]
	v_xor_b32_e32 v12, v12, v10
	v_xor_b32_e32 v1, v1, v13
	v_cvt_pk_bf16_f32 v4, v18, v19
	v_lshlrev_b32_e32 v18, 16, v5
	v_and_b32_e32 v19, 0xffff0000, v5
	v_lshlrev_b32_e32 v20, 16, v81
	v_and_b32_e32 v21, 0xffff0000, v81
	v_xor_b32_e32 v12, v12, v144
	v_xor_b32_e32 v1, v1, v10
	v_pk_mul_f32 v[18:19], v[20:21], v[18:19]
	s_mov_b32 s9, 0
	v_lshlrev_b32_e32 v12, 4, v12
	v_xor_b32_e32 v1, v1, v146
	v_cvt_pk_bf16_f32 v5, v18, v19
	v_lshl_add_u64 v[18:19], s[36:37], 0, v[138:139]
	v_lshlrev_b32_e32 v11, 7, v144
	v_and_b32_e32 v12, 0x70, v12
	v_lshlrev_b32_e32 v1, 4, v1
	v_lshl_add_u64 v[18:19], v[18:19], 0, s[8:9]
	v_mov_b32_e32 v131, 0
	v_add3_u32 v11, s0, v11, v12
	v_lshlrev_b32_e32 v12, 7, v146
	v_and_b32_e32 v1, 0x70, v1
	v_lshl_add_u64 v[18:19], v[18:19], 0, v[130:131]
	v_add3_u32 v1, s0, v12, v1
	ds_read_b128 v[10:13], v11
	ds_read_b128 v[14:17], v1
	global_store_dwordx4 v[18:19], v[2:5], off offset:1536
	s_waitcnt lgkmcnt(2)
	s_nop 0
	v_lshlrev_b32_e32 v2, 16, v6
	v_and_b32_e32 v3, 0xffff0000, v6
	v_lshlrev_b32_e32 v4, 16, v74
	v_and_b32_e32 v5, 0xffff0000, v74
	v_pk_mul_f32 v[2:3], v[4:5], v[2:3]
	v_lshlrev_b32_e32 v4, 16, v7
	v_and_b32_e32 v5, 0xffff0000, v7
	v_lshlrev_b32_e32 v6, 16, v75
	v_and_b32_e32 v7, 0xffff0000, v75
	v_pk_mul_f32 v[4:5], v[6:7], v[4:5]
	v_cvt_pk_bf16_f32 v2, v2, v3
	v_cvt_pk_bf16_f32 v3, v4, v5
	v_lshlrev_b32_e32 v4, 16, v8
	v_and_b32_e32 v5, 0xffff0000, v8
	v_lshlrev_b32_e32 v6, 16, v76
	v_and_b32_e32 v7, 0xffff0000, v76
	v_pk_mul_f32 v[4:5], v[6:7], v[4:5]
	v_lshlrev_b32_e32 v6, 16, v9
	v_and_b32_e32 v7, 0xffff0000, v9
	v_lshlrev_b32_e32 v8, 16, v77
	v_and_b32_e32 v9, 0xffff0000, v77
	v_pk_mul_f32 v[6:7], v[8:9], v[6:7]
	v_cvt_pk_bf16_f32 v4, v4, v5
	v_cvt_pk_bf16_f32 v5, v6, v7
	v_lshl_add_u64 v[6:7], s[36:37], 0, v[136:137]
	v_lshl_add_u64 v[6:7], v[6:7], 0, s[8:9]
	v_lshl_add_u64 v[6:7], v[6:7], 0, v[130:131]
	global_store_dwordx4 v[6:7], v[2:5], off offset:1536
	v_lshlrev_b32_e32 v6, 16, v71
	v_and_b32_e32 v7, 0xffff0000, v71
	s_waitcnt lgkmcnt(1)
	v_lshlrev_b32_e32 v2, 16, v10
	v_and_b32_e32 v3, 0xffff0000, v10
	v_lshlrev_b32_e32 v4, 16, v70
	v_and_b32_e32 v5, 0xffff0000, v70
	v_pk_mul_f32 v[2:3], v[4:5], v[2:3]
	v_lshlrev_b32_e32 v4, 16, v11
	v_and_b32_e32 v5, 0xffff0000, v11
	v_pk_mul_f32 v[4:5], v[6:7], v[4:5]
	v_cvt_pk_bf16_f32 v2, v2, v3
	v_cvt_pk_bf16_f32 v3, v4, v5
	v_lshlrev_b32_e32 v4, 16, v12
	v_and_b32_e32 v5, 0xffff0000, v12
	v_lshlrev_b32_e32 v6, 16, v72
	v_and_b32_e32 v7, 0xffff0000, v72
	v_pk_mul_f32 v[4:5], v[6:7], v[4:5]
	v_lshlrev_b32_e32 v6, 16, v13
	v_and_b32_e32 v7, 0xffff0000, v13
	v_lshlrev_b32_e32 v8, 16, v73
	v_and_b32_e32 v9, 0xffff0000, v73
	v_pk_mul_f32 v[6:7], v[8:9], v[6:7]
	v_cvt_pk_bf16_f32 v4, v4, v5
	v_cvt_pk_bf16_f32 v5, v6, v7
	v_lshl_add_u64 v[6:7], s[36:37], 0, v[134:135]
	v_lshl_add_u64 v[6:7], v[6:7], 0, s[8:9]
	v_lshl_add_u64 v[6:7], v[6:7], 0, v[130:131]
	global_store_dwordx4 v[6:7], v[2:5], off offset:1536
	v_lshlrev_b32_e32 v6, 16, v67
	v_and_b32_e32 v7, 0xffff0000, v67
	s_waitcnt lgkmcnt(0)
	v_lshlrev_b32_e32 v2, 16, v14
	v_and_b32_e32 v3, 0xffff0000, v14
	v_lshlrev_b32_e32 v4, 16, v66
	v_and_b32_e32 v5, 0xffff0000, v66
	v_pk_mul_f32 v[2:3], v[4:5], v[2:3]
	v_lshlrev_b32_e32 v4, 16, v15
	v_and_b32_e32 v5, 0xffff0000, v15
	v_pk_mul_f32 v[4:5], v[6:7], v[4:5]
	v_cvt_pk_bf16_f32 v2, v2, v3
	v_cvt_pk_bf16_f32 v3, v4, v5
	v_lshlrev_b32_e32 v4, 16, v16
	v_and_b32_e32 v5, 0xffff0000, v16
	v_lshlrev_b32_e32 v6, 16, v68
	v_and_b32_e32 v7, 0xffff0000, v68
	v_pk_mul_f32 v[4:5], v[6:7], v[4:5]
	v_lshlrev_b32_e32 v6, 16, v17
	v_and_b32_e32 v7, 0xffff0000, v17
	v_lshlrev_b32_e32 v8, 16, v69
	v_and_b32_e32 v9, 0xffff0000, v69
	v_pk_mul_f32 v[6:7], v[8:9], v[6:7]
	v_cvt_pk_bf16_f32 v4, v4, v5
	v_cvt_pk_bf16_f32 v5, v6, v7
	v_lshl_add_u64 v[6:7], s[36:37], 0, v[132:133]
	v_lshl_add_u64 v[6:7], v[6:7], 0, s[8:9]
	v_lshl_add_u64 v[6:7], v[6:7], 0, v[130:131]
	global_store_dwordx4 v[6:7], v[2:5], off offset:1536
	s_setprio 0
	s_and_saveexec_b64 s[0:1], s[56:57]
	s_cbranch_execz .LBB0_695

; #define LAS __attribute__((address_space(3)))
; DI int q_next(gu32* ctr, volatile LAS int* slot, int tid) {
;     __syncthreads();
;     if (tid == 0) *slot = (int)__hip_atomic_fetch_add(ctr, 1u, RLX_AGENT);
;     __syncthreads();
;     return *slot;
; __global__ void __launch_bounds__(NT, 2) fwd(Args args) {
;     ...
;         for (int r2 = 0; r2 < ((SEQ_P2A & 4) ? 2 : 1); ++r2) for (;;) { const int u = __builtin_amdgcn_readfirstlane(q_next(ctl + CW_Q0 + (pass * 8 + 4 + r2) * 64, slot, tid)); if (u >= 256) break;
.LBB0_790:
	s_setprio 0
	s_waitcnt vmcnt(0)
	s_barrier
	s_and_saveexec_b64 s[0:1], s[56:57]
	s_cbranch_execz .LBB0_794
	s_mov_b64 s[14:15], exec
	v_mbcnt_lo_u32_b32 v2, s14, 0
	v_mbcnt_hi_u32_b32 v2, s15, v2
	v_cmp_eq_u32_e32 vcc, 0, v2
	s_and_saveexec_b64 s[2:3], vcc
	s_cbranch_execz .LBB0_793
	s_bcnt1_i32_b64 s6, s[14:15]
	v_mov_b32_e32 v4, s6
	global_atomic_add v4, v3, v4, s[4:5] sc0

; DI v2u pack4(f32x4 a) { v2u w; w.x = cvtpk(a[0], a[1]); w.y = cvtpk(a[2], a[3]); return w; }
; DI f32x4 unpack4(v2u w) { return (f32x4){bflo(w.x), bfhi(w.x), bflo(w.y), bfhi(w.y)}; }
; DI void unit_memattn(int u, const bf16* __restrict__ MQ, const bf16* __restrict__ MK, const bf16* __restrict__ MV, const bf16* __restrict__ G, bf16* __restrict__ MIX, const bf16* __restrict__ CB, const bf16* __restrict__ U, const float* __restrict__ convw, ...
;     asm volatile("" : "+v"(lane), "+v"(tid));
;     const int b = u >> 7, hm = (u >> 5) & 3, qb = u & 31;
;     const long goff0 = ((long)b * 256) * 256 + hm * 64;
;     v4u fk[4], fv[4], gv[4];
; #pragma unroll
;     for (int i = 0; i < 4; ++i) { const int id = tid + NT * i, j = id >> 3, ch = id & 7;
;         fk[i] = *(const v4u*)(MK + goff0 + (long)j * 256 + ch * 8); fv[i] = *(const v4u*)(MV + goff0 + (long)j * 256 + ch * 8);
;         gv[i] = *(const v4u*)(G + ((size_t)b * SEQ + qb * 256 + j) * D + 768 + hm * 64 + ch * 8); }
;     {   const int c4 = hm * 64 + (tid & 15) * 4;
;         const f32x4 w0 = *(const f32x4*)(convw + c4), w1 = *(const f32x4*)(convw + 256 + c4), w2 = *(const f32x4*)(convw + 512 + c4);
; #pragma unroll 4
;         for (int rl = tid >> 4; rl < 256; rl += NT / 16) { const size_t r2 = (size_t)b * SEQ + qb * 256 + rl; const int t = (int)(r2 & (SEQ - 1));
;             const f32x4 cb = unpack4(*(const v2u*)(CB + r2 * 256 + c4)), u0 = unpack4(*(const v2u*)(U + r2 * 256 + c4));
;             f32x4 u1 = (f32x4){0.f, 0.f, 0.f, 0.f}, u2 = u1;
;             if (t >= 1) u1 = unpack4(*(const v2u*)(U + (r2 - 1) * 256 + c4));
;             if (t >= 2) u2 = unpack4(*(const v2u*)(U + (r2 - 2) * 256 + c4));
;             const f32x4 gg = unpack4(*(const v2u*)(G + r2 * D + c4));
;             *(v2u*)(MIX + r2 * D + c4) = pack4(cb * (w0 * u2 + w1 * u1 + w2 * u0) * gg); }
.LBB0_794:
	s_or_b64 exec, exec, s[0:1]
	s_waitcnt lgkmcnt(0)
	s_barrier
	ds_read_b32 v2, v152
	s_mov_b64 s[0:1], -1
	s_waitcnt lgkmcnt(0)
	v_readfirstlane_b32 s3, v2
	s_cmpk_gt_i32 s3, 0xff
	s_cbranch_scc1 .LBB0_789
	s_cmp_lt_u32 s33, 4
	s_cbranch_scc1 .Lxprio_lo
	s_setprio 2
.Lxprio_lo:
	s_ashr_i32 s14, s3, 7
	s_lshl_b32 s0, s3, 1
	s_ashr_i32 s15, s14, 31
	s_and_b32 s2, s0, 0xc0
	s_lshl_b64 s[0:1], s[14:15], 17
	s_lshl_b32 s6, s2, 1
	s_or_b32 s0, s0, s6
	v_mov_b32_e32 v153, v0
	v_mov_b32_e32 v154, v182
	s_add_u32 s16, s55, s0
	s_addc_u32 s17, s46, s1
	v_lshlrev_b32_e32 v2, 3, v153
	v_and_b32_e32 v2, 56, v2
	s_add_u32 s0, s47, s0
	v_lshlrev_b32_e32 v132, 1, v2
	v_mov_b32_e32 v133, v3
	s_addc_u32 s1, s48, s1
	s_lshl_b32 s3, s3, 8
	v_lshl_add_u64 v[32:33], s[0:1], 0, v[132:133]
	s_lshl_b64 s[0:1], s[14:15], 13
	s_and_b32 s15, s3, 0x1f00
	v_ashrrev_i32_e32 v142, 3, v153
	v_lshl_add_u64 v[28:29], s[16:17], 0, v[132:133]
	s_or_b32 s16, s0, s15
	s_mov_b32 s17, s1
	v_ashrrev_i32_e32 v143, 31, v142
	v_lshlrev_b64 v[4:5], 9, v[142:143]
	v_lshl_add_u64 v[12:13], s[16:17], 0, v[142:143]
	v_add_u32_e32 v143, 0x200, v153
	v_ashrrev_i32_e32 v144, 3, v143
	v_ashrrev_i32_e32 v145, 31, v144
	v_lshl_add_u64 v[18:19], s[16:17], 0, v[144:145]
	v_lshlrev_b64 v[140:141], 11, v[12:13]
	v_lshlrev_b64 v[138:139], 11, v[18:19]
	v_lshl_add_u64 v[12:13], s[24:25], 0, v[140:141]
	v_lshlrev_b64 v[16:17], 9, v[144:145]
	v_lshl_add_u64 v[18:19], s[24:25], 0, v[138:139]
	v_add_u32_e32 v145, 0x400, v153
	v_lshl_add_u64 v[12:13], v[12:13], 0, s[6:7]
	v_lshl_add_u64 v[18:19], v[18:19], 0, s[6:7]
	v_ashrrev_i32_e32 v146, 3, v145
	v_lshl_add_u64 v[6:7], v[28:29], 0, v[4:5]
	v_lshl_add_u64 v[8:9], v[32:33], 0, v[4:5]
	v_lshl_add_u64 v[12:13], v[12:13], 0, v[132:133]
	v_lshl_add_u64 v[14:15], v[28:29], 0, v[16:17]
	v_lshl_add_u64 v[16:17], v[32:33], 0, v[16:17]
	v_lshl_add_u64 v[20:21], v[18:19], 0, v[132:133]
	v_ashrrev_i32_e32 v147, 31, v146
	global_load_dwordx4 v[4:7], v[6:7], off
	s_nop 0
	global_load_dwordx4 v[8:11], v[8:9], off
	s_nop 0
	global_load_dwordx4 v[80:83], v[12:13], off offset:1536
	s_nop 0
	global_load_dwordx4 v[12:15], v[14:15], off
	s_nop 0
	global_load_dwordx4 v[16:19], v[16:17], off
	s_nop 0
	global_load_dwordx4 v[76:79], v[20:21], off offset:1536
	v_lshlrev_b64 v[20:21], 9, v[146:147]
	v_lshl_add_u64 v[30:31], s[16:17], 0, v[146:147]
	v_add_u32_e32 v147, 0x600, v153
	v_ashrrev_i32_e32 v148, 3, v147
	v_ashrrev_i32_e32 v149, 31, v148
	v_lshlrev_b64 v[34:35], 9, v[148:149]
	v_lshl_add_u64 v[22:23], v[28:29], 0, v[20:21]
	v_lshl_add_u64 v[24:25], v[32:33], 0, v[20:21]
	v_lshlrev_b64 v[136:137], 11, v[30:31]
	v_lshl_add_u64 v[28:29], v[28:29], 0, v[34:35]
	v_lshl_add_u64 v[32:33], v[32:33], 0, v[34:35]
	v_lshl_add_u64 v[34:35], s[16:17], 0, v[148:149]
	v_lshl_add_u64 v[30:31], s[24:25], 0, v[136:137]
	v_lshlrev_b64 v[134:135], 11, v[34:35]
	v_lshl_add_u64 v[30:31], v[30:31], 0, s[6:7]
	v_lshl_add_u64 v[34:35], s[24:25], 0, v[134:135]
	v_lshl_add_u64 v[30:31], v[30:31], 0, v[132:133]
	v_lshl_add_u64 v[34:35], v[34:35], 0, s[6:7]
	global_load_dwordx4 v[20:23], v[22:23], off
	s_nop 0
	global_load_dwordx4 v[24:27], v[24:25], off
	s_nop 0
	global_load_dwordx4 v[72:75], v[30:31], off offset:1536
	s_nop 0
	global_load_dwordx4 v[28:31], v[28:29], off
	v_lshl_add_u64 v[36:37], v[34:35], 0, v[132:133]
	global_load_dwordx4 v[32:35], v[32:33], off
	s_nop 0
	global_load_dwordx4 v[68:71], v[36:37], off offset:1536
	v_ashrrev_i32_e32 v60, 4, v153
	v_cmp_gt_i32_e32 vcc, s28, v60
	s_and_saveexec_b64 s[16:17], vcc
	s_cbranch_execz .LBB0_823
	v_lshlrev_b32_e32 v2, 2, v153
	v_and_or_b32 v2, v2, 60, s2
	v_lshlrev_b32_e32 v104, 2, v2
	global_load_dwordx4 v[36:39], v104, s[68:69]
	global_load_dwordx4 v[40:43], v104, s[68:69] offset:1024
	global_load_dwordx4 v[44:47], v104, s[68:69] offset:2048
	s_lshl_b32 s43, s14, 13
	s_or_b32 s43, s43, s15
	s_lshl_b32 s0, s43, 9
	s_add_u32 s0, s0, 0x3400000
	s_add_u32 s0, s82, s0
	s_addc_u32 s1, s83, 0
	s_add_u32 s2, s0, 0xa00000
	s_addc_u32 s3, s1, 0
	s_lshl_b32 s18, s43, 11
	s_add_u32 s18, s18, 0x8800000
	s_add_u32 s18, s82, s18
	s_addc_u32 s19, s83, 0
	s_add_u32 s20, s18, 0x5800000
	s_addc_u32 s21, s19, 0
	v_lshlrev_b32_e32 v2, 1, v2
	v_add_u32_e32 v107, s15, v60
	v_lshl_add_u32 v104, v60, 9, v2
	v_lshl_add_u32 v105, v60, 11, v2
	v_mov_b32_e32 v106, v105
	global_load_dwordx2 v[48:49], v104, s[0:1]
	global_load_dwordx2 v[50:51], v104, s[2:3]
	global_load_dwordx2 v[52:53], v104, s[2:3] offset:-512
	global_load_dwordx2 v[54:55], v104, s[2:3] offset:-1024
	global_load_dwordx2 v[56:57], v105, s[18:19]
	v_add_u32_e32 v104, 0x4000, v104
	v_add_u32_e32 v105, 0x10000, v105
	global_load_dwordx2 v[58:59], v104, s[0:1]
	global_load_dwordx2 v[60:61], v104, s[2:3]
	global_load_dwordx2 v[62:63], v104, s[2:3] offset:-512
	global_load_dwordx2 v[64:65], v104, s[2:3] offset:-1024
	global_load_dwordx2 v[66:67], v105, s[18:19]
	v_add_u32_e32 v104, 0x4000, v104
	v_add_u32_e32 v105, 0x10000, v105
	global_load_dwordx2 v[84:85], v104, s[0:1]
	global_load_dwordx2 v[86:87], v104, s[2:3]
	global_load_dwordx2 v[88:89], v104, s[2:3] offset:-512
	global_load_dwordx2 v[90:91], v104, s[2:3] offset:-1024
	global_load_dwordx2 v[92:93], v105, s[18:19]
	v_add_u32_e32 v104, 0x4000, v104
	v_add_u32_e32 v105, 0x10000, v105
	global_load_dwordx2 v[94:95], v104, s[0:1]
	global_load_dwordx2 v[96:97], v104, s[2:3]
	global_load_dwordx2 v[98:99], v104, s[2:3] offset:-512
	global_load_dwordx2 v[100:101], v104, s[2:3] offset:-1024
	global_load_dwordx2 v[102:103], v105, s[18:19]
	v_add_u32_e32 v104, 0x4000, v104
	v_add_u32_e32 v105, 0x10000, v105
	s_waitcnt vmcnt(15)
; DI v2u pack4(f32x4 a) { v2u w; w.x = cvtpk(a[0], a[1]); w.y = cvtpk(a[2], a[3]); return w; }
; DI f32x4 unpack4(v2u w) { return (f32x4){bflo(w.x), bfhi(w.x), bflo(w.y), bfhi(w.y)}; }
; DI void unit_memattn(int u, const bf16* __restrict__ MQ, const bf16* __restrict__ MK, const bf16* __restrict__ MV, const bf16* __restrict__ G, bf16* __restrict__ MIX, const bf16* __restrict__ CB, const bf16* __restrict__ U, const float* __restrict__ convw, ...
;     ...
; #pragma unroll 4
;         for (int rl = tid >> 4; rl < 256; rl += NT / 16) { const size_t r2 = (size_t)b * SEQ + qb * 256 + rl; const int t = (int)(r2 & (SEQ - 1));
;             const f32x4 cb = unpack4(*(const v2u*)(CB + r2 * 256 + c4)), u0 = unpack4(*(const v2u*)(U + r2 * 256 + c4));
;             f32x4 u1 = (f32x4){0.f, 0.f, 0.f, 0.f}, u2 = u1;
;             if (t >= 1) u1 = unpack4(*(const v2u*)(U + (r2 - 1) * 256 + c4));
;             if (t >= 2) u2 = unpack4(*(const v2u*)(U + (r2 - 2) * 256 + c4));
;             const f32x4 gg = unpack4(*(const v2u*)(G + r2 * D + c4));
;             *(v2u*)(MIX + r2 * D + c4) = pack4(cb * (w0 * u2 + w1 * u1 + w2 * u0) * gg); }
	v_cmp_ne_u32_e32 vcc, 0, v107
	s_nop 1
	v_cndmask_b32_e32 v52, v3, v52, vcc
	v_cndmask_b32_e32 v53, v3, v53, vcc
	v_cmp_lt_u32_e32 vcc, 1, v107
	s_nop 1
	v_cndmask_b32_e32 v54, v3, v54, vcc
	v_cndmask_b32_e32 v55, v3, v55, vcc
	v_lshlrev_b32_e32 v108, 16, v54
	v_and_b32_e32 v109, 0xffff0000, v54
	v_lshlrev_b32_e32 v110, 16, v55
	v_and_b32_e32 v111, 0xffff0000, v55
	v_pk_mul_f32 v[114:115], v[38:39], v[110:111]
	v_pk_mul_f32 v[112:113], v[36:37], v[108:109]
	v_lshlrev_b32_e32 v108, 16, v52
	v_and_b32_e32 v109, 0xffff0000, v52
	v_lshlrev_b32_e32 v110, 16, v53
	v_and_b32_e32 v111, 0xffff0000, v53
	v_pk_fma_f32 v[112:113], v[40:41], v[108:109], v[112:113]
	v_pk_fma_f32 v[114:115], v[42:43], v[110:111], v[114:115]
	v_lshlrev_b32_e32 v108, 16, v50
	v_and_b32_e32 v109, 0xffff0000, v50
	v_lshlrev_b32_e32 v110, 16, v51
	v_and_b32_e32 v111, 0xffff0000, v51
	v_pk_fma_f32 v[114:115], v[46:47], v[110:111], v[114:115]
	v_pk_fma_f32 v[112:113], v[44:45], v[108:109], v[112:113]
	v_lshlrev_b32_e32 v108, 16, v48
	v_and_b32_e32 v109, 0xffff0000, v48
	v_lshlrev_b32_e32 v110, 16, v49
	v_and_b32_e32 v111, 0xffff0000, v49
	v_pk_mul_f32 v[112:113], v[112:113], v[108:109]
	v_pk_mul_f32 v[114:115], v[114:115], v[110:111]
	v_lshlrev_b32_e32 v108, 16, v56
	v_and_b32_e32 v109, 0xffff0000, v56
	v_lshlrev_b32_e32 v110, 16, v57
	v_and_b32_e32 v111, 0xffff0000, v57
	v_pk_mul_f32 v[114:115], v[114:115], v[110:111]
	v_pk_mul_f32 v[112:113], v[112:113], v[108:109]
	s_nop 0
	v_cvt_pk_bf16_f32 v116, v112, v113
	v_cvt_pk_bf16_f32 v117, v114, v115
	global_load_dwordx2 v[48:49], v104, s[0:1]
	global_load_dwordx2 v[50:51], v104, s[2:3]
	global_load_dwordx2 v[52:53], v104, s[2:3] offset:-512
	global_load_dwordx2 v[54:55], v104, s[2:3] offset:-1024
	global_load_dwordx2 v[56:57], v105, s[18:19]
	v_add_u32_e32 v104, 0x4000, v104
	v_add_u32_e32 v105, 0x10000, v105
	global_store_dwordx2 v106, v[116:117], s[20:21]
	v_add_u32_e32 v106, 0x10000, v106
	s_waitcnt vmcnt(16)
	v_lshlrev_b32_e32 v108, 16, v64
	v_and_b32_e32 v109, 0xffff0000, v64
	v_lshlrev_b32_e32 v110, 16, v65
	v_and_b32_e32 v111, 0xffff0000, v65
	v_pk_mul_f32 v[114:115], v[38:39], v[110:111]
	v_pk_mul_f32 v[112:113], v[36:37], v[108:109]
	v_lshlrev_b32_e32 v108, 16, v62
	v_and_b32_e32 v109, 0xffff0000, v62
	v_lshlrev_b32_e32 v110, 16, v63
	v_and_b32_e32 v111, 0xffff0000, v63
	v_pk_fma_f32 v[112:113], v[40:41], v[108:109], v[112:113]
	v_pk_fma_f32 v[114:115], v[42:43], v[110:111], v[114:115]
	v_lshlrev_b32_e32 v108, 16, v60
	v_and_b32_e32 v109, 0xffff0000, v60
	v_lshlrev_b32_e32 v110, 16, v61
	v_and_b32_e32 v111, 0xffff0000, v61
	v_pk_fma_f32 v[114:115], v[46:47], v[110:111], v[114:115]
	v_pk_fma_f32 v[112:113], v[44:45], v[108:109], v[112:113]
	v_lshlrev_b32_e32 v108, 16, v58
	v_and_b32_e32 v109, 0xffff0000, v58
	v_lshlrev_b32_e32 v110, 16, v59
	v_and_b32_e32 v111, 0xffff0000, v59
	v_pk_mul_f32 v[112:113], v[112:113], v[108:109]
	v_pk_mul_f32 v[114:115], v[114:115], v[110:111]
	v_lshlrev_b32_e32 v108, 16, v66
	v_and_b32_e32 v109, 0xffff0000, v66
	v_lshlrev_b32_e32 v110, 16, v67
	v_and_b32_e32 v111, 0xffff0000, v67
	v_pk_mul_f32 v[114:115], v[114:115], v[110:111]
	v_pk_mul_f32 v[112:113], v[112:113], v[108:109]
	s_nop 0
	v_cvt_pk_bf16_f32 v116, v112, v113
	v_cvt_pk_bf16_f32 v117, v114, v115
	global_load_dwordx2 v[58:59], v104, s[0:1]
	global_load_dwordx2 v[60:61], v104, s[2:3]
	global_load_dwordx2 v[62:63], v104, s[2:3] offset:-512
	global_load_dwordx2 v[64:65], v104, s[2:3] offset:-1024
	global_load_dwordx2 v[66:67], v105, s[18:19]
	v_add_u32_e32 v104, 0x4000, v104
	v_add_u32_e32 v105, 0x10000, v105
	global_store_dwordx2 v106, v[116:117], s[20:21]
	v_add_u32_e32 v106, 0x10000, v106
	s_waitcnt vmcnt(17)
	v_lshlrev_b32_e32 v108, 16, v90
	v_and_b32_e32 v109, 0xffff0000, v90
	v_lshlrev_b32_e32 v110, 16, v91
	v_and_b32_e32 v111, 0xffff0000, v91
	v_pk_mul_f32 v[114:115], v[38:39], v[110:111]
	v_pk_mul_f32 v[112:113], v[36:37], v[108:109]
	v_lshlrev_b32_e32 v108, 16, v88
	v_and_b32_e32 v109, 0xffff0000, v88
	v_lshlrev_b32_e32 v110, 16, v89
	v_and_b32_e32 v111, 0xffff0000, v89
	v_pk_fma_f32 v[112:113], v[40:41], v[108:109], v[112:113]
	v_pk_fma_f32 v[114:115], v[42:43], v[110:111], v[114:115]
	v_lshlrev_b32_e32 v108, 16, v86
	v_and_b32_e32 v109, 0xffff0000, v86
	v_lshlrev_b32_e32 v110, 16, v87
	v_and_b32_e32 v111, 0xffff0000, v87
	v_pk_fma_f32 v[114:115], v[46:47], v[110:111], v[114:115]
	v_pk_fma_f32 v[112:113], v[44:45], v[108:109], v[112:113]
	v_lshlrev_b32_e32 v108, 16, v84
	v_and_b32_e32 v109, 0xffff0000, v84
	v_lshlrev_b32_e32 v110, 16, v85
	v_and_b32_e32 v111, 0xffff0000, v85
	v_pk_mul_f32 v[112:113], v[112:113], v[108:109]
	v_pk_mul_f32 v[114:115], v[114:115], v[110:111]
	v_lshlrev_b32_e32 v108, 16, v92
	v_and_b32_e32 v109, 0xffff0000, v92
	v_lshlrev_b32_e32 v110, 16, v93
	v_and_b32_e32 v111, 0xffff0000, v93
	v_pk_mul_f32 v[114:115], v[114:115], v[110:111]
	v_pk_mul_f32 v[112:113], v[112:113], v[108:109]
	s_nop 0
	v_cvt_pk_bf16_f32 v116, v112, v113
	v_cvt_pk_bf16_f32 v117, v114, v115
	global_load_dwordx2 v[84:85], v104, s[0:1]
	global_load_dwordx2 v[86:87], v104, s[2:3]
	global_load_dwordx2 v[88:89], v104, s[2:3] offset:-512
	global_load_dwordx2 v[90:91], v104, s[2:3] offset:-1024
	global_load_dwordx2 v[92:93], v105, s[18:19]
	v_add_u32_e32 v104, 0x4000, v104
	v_add_u32_e32 v105, 0x10000, v105
	global_store_dwordx2 v106, v[116:117], s[20:21]
	v_add_u32_e32 v106, 0x10000, v106
	s_waitcnt vmcnt(18)
; DI v2u pack4(f32x4 a) { v2u w; w.x = cvtpk(a[0], a[1]); w.y = cvtpk(a[2], a[3]); return w; }
; DI f32x4 unpack4(v2u w) { return (f32x4){bflo(w.x), bfhi(w.x), bflo(w.y), bfhi(w.y)}; }
; DI void unit_memattn(int u, const bf16* __restrict__ MQ, const bf16* __restrict__ MK, const bf16* __restrict__ MV, const bf16* __restrict__ G, bf16* __restrict__ MIX, const bf16* __restrict__ CB, const bf16* __restrict__ U, const float* __restrict__ convw, ...
;     ...
; #pragma unroll 4
;         for (int rl = tid >> 4; rl < 256; rl += NT / 16) { const size_t r2 = (size_t)b * SEQ + qb * 256 + rl; const int t = (int)(r2 & (SEQ - 1));
;             const f32x4 cb = unpack4(*(const v2u*)(CB + r2 * 256 + c4)), u0 = unpack4(*(const v2u*)(U + r2 * 256 + c4));
;             f32x4 u1 = (f32x4){0.f, 0.f, 0.f, 0.f}, u2 = u1;
;             if (t >= 1) u1 = unpack4(*(const v2u*)(U + (r2 - 1) * 256 + c4));
;             if (t >= 2) u2 = unpack4(*(const v2u*)(U + (r2 - 2) * 256 + c4));
;             const f32x4 gg = unpack4(*(const v2u*)(G + r2 * D + c4));
;             *(v2u*)(MIX + r2 * D + c4) = pack4(cb * (w0 * u2 + w1 * u1 + w2 * u0) * gg); }
	v_lshlrev_b32_e32 v108, 16, v100
	v_and_b32_e32 v109, 0xffff0000, v100
	v_lshlrev_b32_e32 v110, 16, v101
	v_and_b32_e32 v111, 0xffff0000, v101
	v_pk_mul_f32 v[114:115], v[38:39], v[110:111]
	v_pk_mul_f32 v[112:113], v[36:37], v[108:109]
	v_lshlrev_b32_e32 v108, 16, v98
	v_and_b32_e32 v109, 0xffff0000, v98
	v_lshlrev_b32_e32 v110, 16, v99
	v_and_b32_e32 v111, 0xffff0000, v99
	v_pk_fma_f32 v[112:113], v[40:41], v[108:109], v[112:113]
	v_pk_fma_f32 v[114:115], v[42:43], v[110:111], v[114:115]
	v_lshlrev_b32_e32 v108, 16, v96
	v_and_b32_e32 v109, 0xffff0000, v96
	v_lshlrev_b32_e32 v110, 16, v97
	v_and_b32_e32 v111, 0xffff0000, v97
	v_pk_fma_f32 v[114:115], v[46:47], v[110:111], v[114:115]
	v_pk_fma_f32 v[112:113], v[44:45], v[108:109], v[112:113]
	v_lshlrev_b32_e32 v108, 16, v94
	v_and_b32_e32 v109, 0xffff0000, v94
	v_lshlrev_b32_e32 v110, 16, v95
	v_and_b32_e32 v111, 0xffff0000, v95
	v_pk_mul_f32 v[112:113], v[112:113], v[108:109]
	v_pk_mul_f32 v[114:115], v[114:115], v[110:111]
	v_lshlrev_b32_e32 v108, 16, v102
	v_and_b32_e32 v109, 0xffff0000, v102
	v_lshlrev_b32_e32 v110, 16, v103
	v_and_b32_e32 v111, 0xffff0000, v103
	v_pk_mul_f32 v[114:115], v[114:115], v[110:111]
	v_pk_mul_f32 v[112:113], v[112:113], v[108:109]
	s_nop 0
	v_cvt_pk_bf16_f32 v116, v112, v113
	v_cvt_pk_bf16_f32 v117, v114, v115
	global_load_dwordx2 v[94:95], v104, s[0:1]
	global_load_dwordx2 v[96:97], v104, s[2:3]
	global_load_dwordx2 v[98:99], v104, s[2:3] offset:-512
	global_load_dwordx2 v[100:101], v104, s[2:3] offset:-1024
	global_load_dwordx2 v[102:103], v105, s[18:19]
	global_store_dwordx2 v106, v[116:117], s[20:21]
	v_add_u32_e32 v106, 0x10000, v106
	s_waitcnt vmcnt(19)
	v_lshlrev_b32_e32 v108, 16, v54
	v_and_b32_e32 v109, 0xffff0000, v54
	v_lshlrev_b32_e32 v110, 16, v55
	v_and_b32_e32 v111, 0xffff0000, v55
	v_pk_mul_f32 v[114:115], v[38:39], v[110:111]
	v_pk_mul_f32 v[112:113], v[36:37], v[108:109]
	v_lshlrev_b32_e32 v108, 16, v52
	v_and_b32_e32 v109, 0xffff0000, v52
	v_lshlrev_b32_e32 v110, 16, v53
	v_and_b32_e32 v111, 0xffff0000, v53
	v_pk_fma_f32 v[112:113], v[40:41], v[108:109], v[112:113]
	v_pk_fma_f32 v[114:115], v[42:43], v[110:111], v[114:115]
	v_lshlrev_b32_e32 v108, 16, v50
	v_and_b32_e32 v109, 0xffff0000, v50
	v_lshlrev_b32_e32 v110, 16, v51
	v_and_b32_e32 v111, 0xffff0000, v51
	v_pk_fma_f32 v[114:115], v[46:47], v[110:111], v[114:115]
	v_pk_fma_f32 v[112:113], v[44:45], v[108:109], v[112:113]
	v_lshlrev_b32_e32 v108, 16, v48
	v_and_b32_e32 v109, 0xffff0000, v48
	v_lshlrev_b32_e32 v110, 16, v49
	v_and_b32_e32 v111, 0xffff0000, v49
	v_pk_mul_f32 v[112:113], v[112:113], v[108:109]
	v_pk_mul_f32 v[114:115], v[114:115], v[110:111]
	v_lshlrev_b32_e32 v108, 16, v56
	v_and_b32_e32 v109, 0xffff0000, v56
	v_lshlrev_b32_e32 v110, 16, v57
	v_and_b32_e32 v111, 0xffff0000, v57
	v_pk_mul_f32 v[114:115], v[114:115], v[110:111]
	v_pk_mul_f32 v[112:113], v[112:113], v[108:109]
	s_nop 0
	v_cvt_pk_bf16_f32 v116, v112, v113
	v_cvt_pk_bf16_f32 v117, v114, v115
	global_store_dwordx2 v106, v[116:117], s[20:21]
	v_add_u32_e32 v106, 0x10000, v106
	s_waitcnt vmcnt(14)
; DI v2u pack4(f32x4 a) { v2u w; w.x = cvtpk(a[0], a[1]); w.y = cvtpk(a[2], a[3]); return w; }
; DI f32x4 unpack4(v2u w) { return (f32x4){bflo(w.x), bfhi(w.x), bflo(w.y), bfhi(w.y)}; }
; DI void unit_memattn(int u, const bf16* __restrict__ MQ, const bf16* __restrict__ MK, const bf16* __restrict__ MV, const bf16* __restrict__ G, bf16* __restrict__ MIX, const bf16* __restrict__ CB, const bf16* __restrict__ U, const float* __restrict__ convw, ...
;     ...
;         for (int rl = tid >> 4; rl < 256; rl += NT / 16) { const size_t r2 = (size_t)b * SEQ + qb * 256 + rl; const int t = (int)(r2 & (SEQ - 1));
;             const f32x4 cb = unpack4(*(const v2u*)(CB + r2 * 256 + c4)), u0 = unpack4(*(const v2u*)(U + r2 * 256 + c4));
;             f32x4 u1 = (f32x4){0.f, 0.f, 0.f, 0.f}, u2 = u1;
;             if (t >= 1) u1 = unpack4(*(const v2u*)(U + (r2 - 1) * 256 + c4));
;             if (t >= 2) u2 = unpack4(*(const v2u*)(U + (r2 - 2) * 256 + c4));
;             const f32x4 gg = unpack4(*(const v2u*)(G + r2 * D + c4));
;             *(v2u*)(MIX + r2 * D + c4) = pack4(cb * (w0 * u2 + w1 * u1 + w2 * u0) * gg); }
	v_lshlrev_b32_e32 v108, 16, v64
	v_and_b32_e32 v109, 0xffff0000, v64
	v_lshlrev_b32_e32 v110, 16, v65
	v_and_b32_e32 v111, 0xffff0000, v65
	v_pk_mul_f32 v[114:115], v[38:39], v[110:111]
	v_pk_mul_f32 v[112:113], v[36:37], v[108:109]
	v_lshlrev_b32_e32 v108, 16, v62
	v_and_b32_e32 v109, 0xffff0000, v62
	v_lshlrev_b32_e32 v110, 16, v63
	v_and_b32_e32 v111, 0xffff0000, v63
	v_pk_fma_f32 v[112:113], v[40:41], v[108:109], v[112:113]
	v_pk_fma_f32 v[114:115], v[42:43], v[110:111], v[114:115]
	v_lshlrev_b32_e32 v108, 16, v60
	v_and_b32_e32 v109, 0xffff0000, v60
	v_lshlrev_b32_e32 v110, 16, v61
	v_and_b32_e32 v111, 0xffff0000, v61
	v_pk_fma_f32 v[114:115], v[46:47], v[110:111], v[114:115]
	v_pk_fma_f32 v[112:113], v[44:45], v[108:109], v[112:113]
	v_lshlrev_b32_e32 v108, 16, v58
	v_and_b32_e32 v109, 0xffff0000, v58
	v_lshlrev_b32_e32 v110, 16, v59
	v_and_b32_e32 v111, 0xffff0000, v59
	v_pk_mul_f32 v[112:113], v[112:113], v[108:109]
	v_pk_mul_f32 v[114:115], v[114:115], v[110:111]
	v_lshlrev_b32_e32 v108, 16, v66
	v_and_b32_e32 v109, 0xffff0000, v66
	v_lshlrev_b32_e32 v110, 16, v67
	v_and_b32_e32 v111, 0xffff0000, v67
	v_pk_mul_f32 v[114:115], v[114:115], v[110:111]
	v_pk_mul_f32 v[112:113], v[112:113], v[108:109]
	s_nop 0
	v_cvt_pk_bf16_f32 v116, v112, v113
	v_cvt_pk_bf16_f32 v117, v114, v115
	global_store_dwordx2 v106, v[116:117], s[20:21]
	v_add_u32_e32 v106, 0x10000, v106
	s_waitcnt vmcnt(9)
	v_lshlrev_b32_e32 v108, 16, v90
	v_and_b32_e32 v109, 0xffff0000, v90
	v_lshlrev_b32_e32 v110, 16, v91
	v_and_b32_e32 v111, 0xffff0000, v91
	v_pk_mul_f32 v[114:115], v[38:39], v[110:111]
	v_pk_mul_f32 v[112:113], v[36:37], v[108:109]
	v_lshlrev_b32_e32 v108, 16, v88
	v_and_b32_e32 v109, 0xffff0000, v88
	v_lshlrev_b32_e32 v110, 16, v89
	v_and_b32_e32 v111, 0xffff0000, v89
	v_pk_fma_f32 v[112:113], v[40:41], v[108:109], v[112:113]
	v_pk_fma_f32 v[114:115], v[42:43], v[110:111], v[114:115]
	v_lshlrev_b32_e32 v108, 16, v86
	v_and_b32_e32 v109, 0xffff0000, v86
	v_lshlrev_b32_e32 v110, 16, v87
	v_and_b32_e32 v111, 0xffff0000, v87
	v_pk_fma_f32 v[114:115], v[46:47], v[110:111], v[114:115]
	v_pk_fma_f32 v[112:113], v[44:45], v[108:109], v[112:113]
	v_lshlrev_b32_e32 v108, 16, v84
	v_and_b32_e32 v109, 0xffff0000, v84
	v_lshlrev_b32_e32 v110, 16, v85
	v_and_b32_e32 v111, 0xffff0000, v85
	v_pk_mul_f32 v[112:113], v[112:113], v[108:109]
	v_pk_mul_f32 v[114:115], v[114:115], v[110:111]
	v_lshlrev_b32_e32 v108, 16, v92
	v_and_b32_e32 v109, 0xffff0000, v92
	v_lshlrev_b32_e32 v110, 16, v93
	v_and_b32_e32 v111, 0xffff0000, v93
	v_pk_mul_f32 v[114:115], v[114:115], v[110:111]
	v_pk_mul_f32 v[112:113], v[112:113], v[108:109]
	s_nop 0
	v_cvt_pk_bf16_f32 v116, v112, v113
	v_cvt_pk_bf16_f32 v117, v114, v115
	global_store_dwordx2 v106, v[116:117], s[20:21]
	v_add_u32_e32 v106, 0x10000, v106
	s_waitcnt vmcnt(4)
	v_lshlrev_b32_e32 v108, 16, v100
	v_and_b32_e32 v109, 0xffff0000, v100
	v_lshlrev_b32_e32 v110, 16, v101
	v_and_b32_e32 v111, 0xffff0000, v101
	v_pk_mul_f32 v[114:115], v[38:39], v[110:111]
	v_pk_mul_f32 v[112:113], v[36:37], v[108:109]
	v_lshlrev_b32_e32 v108, 16, v98
	v_and_b32_e32 v109, 0xffff0000, v98
	v_lshlrev_b32_e32 v110, 16, v99
	v_and_b32_e32 v111, 0xffff0000, v99
	v_pk_fma_f32 v[112:113], v[40:41], v[108:109], v[112:113]
	v_pk_fma_f32 v[114:115], v[42:43], v[110:111], v[114:115]
	v_lshlrev_b32_e32 v108, 16, v96
	v_and_b32_e32 v109, 0xffff0000, v96
	v_lshlrev_b32_e32 v110, 16, v97
	v_and_b32_e32 v111, 0xffff0000, v97
	v_pk_fma_f32 v[114:115], v[46:47], v[110:111], v[114:115]
	v_pk_fma_f32 v[112:113], v[44:45], v[108:109], v[112:113]
	v_lshlrev_b32_e32 v108, 16, v94
	v_and_b32_e32 v109, 0xffff0000, v94
	v_lshlrev_b32_e32 v110, 16, v95
	v_and_b32_e32 v111, 0xffff0000, v95
	v_pk_mul_f32 v[112:113], v[112:113], v[108:109]
	v_pk_mul_f32 v[114:115], v[114:115], v[110:111]
	v_lshlrev_b32_e32 v108, 16, v102
	v_and_b32_e32 v109, 0xffff0000, v102
	v_lshlrev_b32_e32 v110, 16, v103
	v_and_b32_e32 v111, 0xffff0000, v103
	v_pk_mul_f32 v[114:115], v[114:115], v[110:111]
	v_pk_mul_f32 v[112:113], v[112:113], v[108:109]
	s_nop 0
	v_cvt_pk_bf16_f32 v116, v112, v113
	v_cvt_pk_bf16_f32 v117, v114, v115
	global_store_dwordx2 v106, v[116:117], s[20:21]
